# software prefetch: each GLA-prep item touches the next item's code/q/k lines so the next item's head loads hit L2
# speedup vs baseline: 1.0047x; 1.0047x over previous
; DI void gla_prep_item(const Args& A, int l, unsigned char* ldsb, int item, int tid, bool stage) {
;     ...
;     const bf16* CODES = (const bf16*)(R + R_CODES); const bf16* GQK = (const bf16*)(R + R_GQK);
;     bf16* GP = (bf16*)(R + R_GP); bf16* KT = (bf16*)(R + R_KT); float* DEC = (float*)(R + R_DEC);
;     const int c = item & 63, bh = item >> 6, h = bh & 3, b = bh >> 2;
;     const size_t tok0 = (size_t)b * SEQ + c * 64;
;     const int t = tid >> 3, dg = tid & 7;
;     const u32x4* cp = (const u32x4*)(CODES + (tok0 + t) * 32);
;     const u32x4 cq0 = cp[0], cq1 = cp[1], cq2 = cp[2], cq3 = cp[3];
;     const u32x4 qv = *(const u32x4*)(GQK + (tok0 + t) * 512 + h * 64 + 8 * dg), kv = *(const u32x4*)(GQK + (tok0 + t) * 512 + 256 + h * 64 + 8 * dg);
.LBB0_560:
	v_readlane_b32 s2, v244, 3
	s_add_i32 s2, s2, s10
	s_ashr_i32 s2, s2, 2
	s_and_b32 s2, s2, -8
	v_readlane_b32 s3, v245, 3
	s_or_b32 s8, s3, s2
	v_readlane_b32 s2, v245, 4
	v_readlane_b32 s3, v245, 5
	s_and_b64 s[2:3], s[2:3], exec
	s_cselect_b32 s2, s8, s10
	v_readlane_b32 s3, v246, 62
	s_or_b32 s8, s2, s3
	s_and_b64 s[2:3], s[6:7], exec
	s_cselect_b32 s31, s8, s10
	s_movk_i32 s2, 0xa8
	s_mov_b32 s14, s29
	s_bfe_u32 s29, s31, 0x20006
	s_ashr_i32 s3, s2, 31
	s_add_u32 s2, s0, s2
	s_addc_u32 s3, s1, s3
	s_ashr_i32 s12, s31, 8
	s_ashr_i32 s13, s12, 31
	s_lshl_b32 s8, s31, 6
	s_load_dwordx2 s[62:63], s[2:3], 0x0
	s_lshl_b64 s[60:61], s[12:13], 12
	s_and_b32 s40, s8, 0xfc0
	s_or_b32 s60, s60, s40
	v_lshl_add_u64 v[48:49], s[60:61], 0, v[26:27]
	v_lshlrev_b64 v[2:3], 6, v[48:49]
	s_waitcnt lgkmcnt(0)
	v_lshl_add_u64 v[2:3], s[62:63], 0, v[2:3]
	s_mov_b64 s[2:3], 0x1f600000
	v_lshl_add_u64 v[4:5], v[2:3], 0, s[2:3]
	s_mov_b32 s2, 0x1f600000
	v_add_co_u32_e32 v2, vcc, s2, v2
	s_and_b32 s30, s31, 0xc0
	s_nop 0
	v_addc_co_u32_e32 v3, vcc, 0, v3, vcc
	global_load_dwordx4 v[22:25], v[2:3], off
	global_load_dwordx4 v[10:13], v[4:5], off offset:48
	global_load_dwordx4 v[14:17], v[4:5], off offset:32
	global_load_dwordx4 v[18:21], v[4:5], off offset:16
	v_add_co_u32_e32 v90, vcc, 0x8000, v4
	s_nop 1
	v_addc_co_u32_e32 v91, vcc, 0, v5, vcc
	v_lshlrev_b64 v[2:3], 10, v[48:49]
	s_lshl_b32 s8, s30, 1
	v_lshl_add_u64 v[2:3], s[62:63], 0, v[2:3]
	v_lshl_add_u64 v[2:3], v[2:3], 0, s[8:9]
	v_lshlrev_b32_e32 v0, 1, v28
	v_lshl_add_u64 v[2:3], v[2:3], 0, v[0:1]
	s_mov_b64 s[2:3], 0x1b600000
	v_lshl_add_u64 v[4:5], v[2:3], 0, s[2:3]
	v_add_co_u32_e32 v2, vcc, 0x1b600000, v2
	s_cmp_eq_u32 s29, s14
	s_nop 0
	v_addc_co_u32_e32 v3, vcc, 0, v3, vcc
	v_add_co_u32_e32 v92, vcc, 0x80000, v4
	s_nop 1
	v_addc_co_u32_e32 v93, vcc, 0, v5, vcc
	global_load_dwordx4 v[6:9], v[2:3], off
	s_nop 0
	global_load_dwordx4 v[2:5], v[4:5], off offset:512
	global_load_dword v88, v[90:91], off
	global_load_dword v88, v[92:93], off
	global_load_dword v88, v[92:93], off offset:512
	s_cbranch_scc1 .LBB0_572
	s_and_saveexec_b64 s[2:3], s[42:43]
	s_xor_b64 s[2:3], exec, s[2:3]
	s_cbranch_execz .LBB0_563
	s_movk_i32 s8, 0x58

; DI float bflo(unsigned w) { return __uint_as_float(w << 16); }
; DI float bfhi(unsigned w) { return __uint_as_float(w & 0xffff0000u); }
; DI void gla_prep_item(const Args& A, int l, unsigned char* ldsb, int item, int tid, bool stage) {
;     ...
;     {
;         float cf[32];
; #pragma unroll
;         for (int j = 0; j < 4; ++j) { const u32x4 v = j == 0 ? cq0 : (j == 1 ? cq1 : (j == 2 ? cq2 : cq3)); cf[8 * j + 0] = bflo(v.x); cf[8 * j + 1] = bfhi(v.x); cf[8 * j + 2] = bflo(v.y); cf[8 * j + 3] = bfhi(v.y); cf[8 * j + 4] = bflo(v.z); cf[8 * j + 5] = bfhi(v.z); cf[8 * j + 6] = bflo(v.w); cf[8 * j + 7] = bfhi(v.w); }
; #pragma unroll
;         for (int dir = 0; dir < 2; ++dir) {
;             float z[8];
; #pragma unroll
;             for (int dd = 0; dd < 8; ++dd) z[dd] = bg[dir * 64 + 8 * dg + dd];
; #pragma unroll
;             for (int r = 0; r < 16; ++r) {
;                 const f32x4 w0 = *(const f32x4*)(wg + dir * 1024 + r * 64 + 8 * dg), w1 = *(const f32x4*)(wg + dir * 1024 + r * 64 + 8 * dg + 4);
;                 const float cv = cf[dir * 16 + r];
;                 z[0] += cv * w0[0]; z[1] += cv * w0[1]; z[2] += cv * w0[2]; z[3] += cv * w0[3]; z[4] += cv * w1[0]; z[5] += cv * w1[1]; z[6] += cv * w1[2]; z[7] += cv * w1[3];
;             }
.LBB0_572:
	s_waitcnt vmcnt(5)
	ds_read_b128 v[94:97], v35 offset:43520
	ds_read_b128 v[98:101], v35 offset:43536
	ds_read_b128 v[118:121], v35 offset:35328
	ds_read_b128 v[122:125], v35 offset:35344
	ds_read_b128 v[126:129], v35 offset:35584
	ds_read_b128 v[130:133], v35 offset:35600
	ds_read_b128 v[134:137], v35 offset:35840
	ds_read_b128 v[138:141], v35 offset:35856
	ds_read_b128 v[142:145], v35 offset:36096
	ds_read_b128 v[146:149], v35 offset:36112
	v_lshlrev_b32_e32 v102, 16, v22
	v_and_b32_e32 v103, 0xffff0000, v22
	v_lshlrev_b32_e32 v104, 16, v23
	v_and_b32_e32 v105, 0xffff0000, v23
	v_lshlrev_b32_e32 v106, 16, v24
	v_and_b32_e32 v107, 0xffff0000, v24
	v_lshlrev_b32_e32 v108, 16, v25
	v_and_b32_e32 v109, 0xffff0000, v25
	v_lshlrev_b32_e32 v110, 16, v18
	v_and_b32_e32 v111, 0xffff0000, v18
	v_lshlrev_b32_e32 v112, 16, v19
	v_and_b32_e32 v113, 0xffff0000, v19
	v_lshlrev_b32_e32 v114, 16, v20
	v_and_b32_e32 v115, 0xffff0000, v20
	v_lshlrev_b32_e32 v116, 16, v21
	v_and_b32_e32 v117, 0xffff0000, v21
	s_waitcnt lgkmcnt(6)
	v_fmac_f32_e32 v94, v118, v102
	v_fmac_f32_e32 v95, v119, v102
	v_fmac_f32_e32 v96, v120, v102
	v_fmac_f32_e32 v97, v121, v102
	v_fmac_f32_e32 v98, v122, v102
	v_fmac_f32_e32 v99, v123, v102
	v_fmac_f32_e32 v100, v124, v102
	v_fmac_f32_e32 v101, v125, v102
	ds_read_b128 v[118:121], v35 offset:36352
	ds_read_b128 v[122:125], v35 offset:36368
	s_waitcnt lgkmcnt(6)
	v_fmac_f32_e32 v94, v126, v103
	v_fmac_f32_e32 v95, v127, v103
	v_fmac_f32_e32 v96, v128, v103
	v_fmac_f32_e32 v97, v129, v103
	v_fmac_f32_e32 v98, v130, v103
	v_fmac_f32_e32 v99, v131, v103
	v_fmac_f32_e32 v100, v132, v103
	v_fmac_f32_e32 v101, v133, v103
	ds_read_b128 v[126:129], v35 offset:36608
	ds_read_b128 v[130:133], v35 offset:36624
	s_waitcnt lgkmcnt(6)
	v_fmac_f32_e32 v94, v134, v104
	v_fmac_f32_e32 v95, v135, v104
	v_fmac_f32_e32 v96, v136, v104
	v_fmac_f32_e32 v97, v137, v104
	v_fmac_f32_e32 v98, v138, v104
	v_fmac_f32_e32 v99, v139, v104
	v_fmac_f32_e32 v100, v140, v104
	v_fmac_f32_e32 v101, v141, v104
	ds_read_b128 v[134:137], v35 offset:36864
	ds_read_b128 v[138:141], v35 offset:36880
	s_waitcnt lgkmcnt(6)
	v_fmac_f32_e32 v94, v142, v105
	v_fmac_f32_e32 v95, v143, v105
	v_fmac_f32_e32 v96, v144, v105
	v_fmac_f32_e32 v97, v145, v105
	v_fmac_f32_e32 v98, v146, v105
	v_fmac_f32_e32 v99, v147, v105
	v_fmac_f32_e32 v100, v148, v105
	v_fmac_f32_e32 v101, v149, v105
	ds_read_b128 v[142:145], v35 offset:37120
	ds_read_b128 v[146:149], v35 offset:37136
	s_waitcnt lgkmcnt(6)
	v_fmac_f32_e32 v94, v118, v106
	v_fmac_f32_e32 v95, v119, v106
	v_fmac_f32_e32 v96, v120, v106
	v_fmac_f32_e32 v97, v121, v106
	v_fmac_f32_e32 v98, v122, v106
	v_fmac_f32_e32 v99, v123, v106
	v_fmac_f32_e32 v100, v124, v106
	v_fmac_f32_e32 v101, v125, v106
	ds_read_b128 v[118:121], v35 offset:37376
	ds_read_b128 v[122:125], v35 offset:37392
	s_waitcnt lgkmcnt(6)
	v_fmac_f32_e32 v94, v126, v107
	v_fmac_f32_e32 v95, v127, v107
	v_fmac_f32_e32 v96, v128, v107
	v_fmac_f32_e32 v97, v129, v107
	v_fmac_f32_e32 v98, v130, v107
	v_fmac_f32_e32 v99, v131, v107
	v_fmac_f32_e32 v100, v132, v107
	v_fmac_f32_e32 v101, v133, v107
	ds_read_b128 v[126:129], v35 offset:37632
	ds_read_b128 v[130:133], v35 offset:37648
	s_waitcnt lgkmcnt(6)
	v_fmac_f32_e32 v94, v134, v108
	v_fmac_f32_e32 v95, v135, v108
	v_fmac_f32_e32 v96, v136, v108
	v_fmac_f32_e32 v97, v137, v108
	v_fmac_f32_e32 v98, v138, v108
	v_fmac_f32_e32 v99, v139, v108
	v_fmac_f32_e32 v100, v140, v108
	v_fmac_f32_e32 v101, v141, v108
	ds_read_b128 v[134:137], v35 offset:37888
	ds_read_b128 v[138:141], v35 offset:37904
	s_waitcnt lgkmcnt(6)
	v_fmac_f32_e32 v94, v142, v109
	v_fmac_f32_e32 v95, v143, v109
	v_fmac_f32_e32 v96, v144, v109
	v_fmac_f32_e32 v97, v145, v109
	v_fmac_f32_e32 v98, v146, v109
	v_fmac_f32_e32 v99, v147, v109
	v_fmac_f32_e32 v100, v148, v109
	v_fmac_f32_e32 v101, v149, v109
	ds_read_b128 v[142:145], v35 offset:38144
	ds_read_b128 v[146:149], v35 offset:38160
	s_waitcnt lgkmcnt(6)
	v_fmac_f32_e32 v94, v118, v110
	v_fmac_f32_e32 v95, v119, v110
	v_fmac_f32_e32 v96, v120, v110
	v_fmac_f32_e32 v97, v121, v110
	v_fmac_f32_e32 v98, v122, v110
	v_fmac_f32_e32 v99, v123, v110
	v_fmac_f32_e32 v100, v124, v110
	v_fmac_f32_e32 v101, v125, v110
	ds_read_b128 v[118:121], v35 offset:38400
	ds_read_b128 v[122:125], v35 offset:38416
	s_waitcnt lgkmcnt(6)
	v_fmac_f32_e32 v94, v126, v111
	v_fmac_f32_e32 v95, v127, v111
	v_fmac_f32_e32 v96, v128, v111
	v_fmac_f32_e32 v97, v129, v111
	v_fmac_f32_e32 v98, v130, v111
	v_fmac_f32_e32 v99, v131, v111
	v_fmac_f32_e32 v100, v132, v111
	v_fmac_f32_e32 v101, v133, v111
	ds_read_b128 v[126:129], v35 offset:38656
	ds_read_b128 v[130:133], v35 offset:38672
	s_waitcnt lgkmcnt(6)
	v_fmac_f32_e32 v94, v134, v112
	v_fmac_f32_e32 v95, v135, v112
	v_fmac_f32_e32 v96, v136, v112
	v_fmac_f32_e32 v97, v137, v112
	v_fmac_f32_e32 v98, v138, v112
	v_fmac_f32_e32 v99, v139, v112
	v_fmac_f32_e32 v100, v140, v112
	v_fmac_f32_e32 v101, v141, v112
	ds_read_b128 v[134:137], v35 offset:38912
	ds_read_b128 v[138:141], v35 offset:38928
	s_waitcnt lgkmcnt(6)
	v_fmac_f32_e32 v94, v142, v113
	v_fmac_f32_e32 v95, v143, v113
	v_fmac_f32_e32 v96, v144, v113
	v_fmac_f32_e32 v97, v145, v113
	v_fmac_f32_e32 v98, v146, v113
	v_fmac_f32_e32 v99, v147, v113
	v_fmac_f32_e32 v100, v148, v113
	v_fmac_f32_e32 v101, v149, v113
	ds_read_b128 v[142:145], v35 offset:39168
	ds_read_b128 v[146:149], v35 offset:39184
	s_waitcnt lgkmcnt(6)
	v_fmac_f32_e32 v94, v118, v114
	v_fmac_f32_e32 v95, v119, v114
	v_fmac_f32_e32 v96, v120, v114
	v_fmac_f32_e32 v97, v121, v114
	v_fmac_f32_e32 v98, v122, v114
	v_fmac_f32_e32 v99, v123, v114
	v_fmac_f32_e32 v100, v124, v114
	v_fmac_f32_e32 v101, v125, v114
	s_waitcnt lgkmcnt(4)
; DI float log_sigmoid_f(float z) { return fminf(z, 0.f) - __logf(1.0f + __expf(-fabsf(z))); }
; DI void gla_prep_item(const Args& A, int l, unsigned char* ldsb, int item, int tid, bool stage) {
;     ...
;             float z[8];
; #pragma unroll
;             for (int dd = 0; dd < 8; ++dd) z[dd] = bg[dir * 64 + 8 * dg + dd];
; #pragma unroll
;             for (int r = 0; r < 16; ++r) {
;                 const f32x4 w0 = *(const f32x4*)(wg + dir * 1024 + r * 64 + 8 * dg), w1 = *(const f32x4*)(wg + dir * 1024 + r * 64 + 8 * dg + 4);
;                 const float cv = cf[dir * 16 + r];
;                 z[0] += cv * w0[0]; z[1] += cv * w0[1]; z[2] += cv * w0[2]; z[3] += cv * w0[3]; z[4] += cv * w1[0]; z[5] += cv * w1[1]; z[6] += cv * w1[2]; z[7] += cv * w1[3];
;             }
; #pragma unroll
;             for (int dd = 0; dd < 8; ++dd) gl[(dir * 64 + t) * 65 + 8 * dg + dd] = log_sigmoid_f(z[dd]) * (1.0f / 16.0f);
	v_fmac_f32_e32 v94, v126, v115
	v_fmac_f32_e32 v95, v127, v115
	v_fmac_f32_e32 v96, v128, v115
	v_fmac_f32_e32 v97, v129, v115
	v_fmac_f32_e32 v98, v130, v115
	v_fmac_f32_e32 v99, v131, v115
	v_fmac_f32_e32 v100, v132, v115
	v_fmac_f32_e32 v101, v133, v115
	s_waitcnt lgkmcnt(2)
	v_fmac_f32_e32 v94, v134, v116
	v_fmac_f32_e32 v95, v135, v116
	v_fmac_f32_e32 v96, v136, v116
	v_fmac_f32_e32 v97, v137, v116
	v_fmac_f32_e32 v98, v138, v116
	v_fmac_f32_e32 v99, v139, v116
	v_fmac_f32_e32 v100, v140, v116
	v_fmac_f32_e32 v101, v141, v116
	s_waitcnt lgkmcnt(0)
	v_fmac_f32_e32 v94, v142, v117
	v_fmac_f32_e32 v95, v143, v117
	v_fmac_f32_e32 v96, v144, v117
	v_fmac_f32_e32 v97, v145, v117
	v_fmac_f32_e32 v98, v146, v117
	v_fmac_f32_e32 v99, v147, v117
	v_fmac_f32_e32 v100, v148, v117
	v_fmac_f32_e32 v101, v149, v117
	v_mul_f32_e64 v118, |v94|, s11
	v_mul_f32_e64 v119, |v95|, s11
	v_mul_f32_e64 v120, |v96|, s11
	v_mul_f32_e64 v121, |v97|, s11
	v_mul_f32_e64 v122, |v98|, s11
	v_mul_f32_e64 v123, |v99|, s11
	v_mul_f32_e64 v124, |v100|, s11
	v_mul_f32_e64 v125, |v101|, s11
	v_exp_f32_e32 v118, v118
	v_exp_f32_e32 v119, v119
	v_exp_f32_e32 v120, v120
	v_exp_f32_e32 v121, v121
	v_exp_f32_e32 v122, v122
	v_exp_f32_e32 v123, v123
	v_exp_f32_e32 v124, v124
	v_exp_f32_e32 v125, v125
	v_min_f32_e32 v142, 0, v94
	v_min_f32_e32 v143, 0, v95
	v_min_f32_e32 v144, 0, v96
	v_min_f32_e32 v145, 0, v97
	v_min_f32_e32 v146, 0, v98
	v_min_f32_e32 v147, 0, v99
	v_min_f32_e32 v148, 0, v100
	v_min_f32_e32 v149, 0, v101
	v_add_f32_e32 v118, 1.0, v118
	v_add_f32_e32 v119, 1.0, v119
	v_add_f32_e32 v120, 1.0, v120
	v_add_f32_e32 v121, 1.0, v121
	v_add_f32_e32 v122, 1.0, v122
	v_add_f32_e32 v123, 1.0, v123
	v_add_f32_e32 v124, 1.0, v124
	v_add_f32_e32 v125, 1.0, v125
	v_log_f32_e32 v126, v118
	v_log_f32_e32 v127, v119
	v_log_f32_e32 v128, v120
	v_log_f32_e32 v129, v121
	v_log_f32_e32 v130, v122
	v_log_f32_e32 v131, v123
	v_log_f32_e32 v132, v124
	v_log_f32_e32 v133, v125
	s_nop 0
	v_mul_f32_e32 v134, 0x3f317217, v126
	v_mul_f32_e32 v135, 0x3f317217, v127
	v_mul_f32_e32 v136, 0x3f317217, v128
	v_mul_f32_e32 v137, 0x3f317217, v129
	v_mul_f32_e32 v138, 0x3f317217, v130
	v_mul_f32_e32 v139, 0x3f317217, v131
	v_mul_f32_e32 v140, 0x3f317217, v132
	v_mul_f32_e32 v141, 0x3f317217, v133
	v_fma_f32 v134, v126, s81, -v134
	v_fma_f32 v135, v127, s81, -v135
	v_fma_f32 v136, v128, s81, -v136
	v_fma_f32 v137, v129, s81, -v137
	v_fma_f32 v138, v130, s81, -v138
	v_fma_f32 v139, v131, s81, -v139
	v_fma_f32 v140, v132, s81, -v140
	v_fma_f32 v141, v133, s81, -v141
	v_fmac_f32_e32 v134, 0x3377d1cf, v126
	v_fmac_f32_e32 v135, 0x3377d1cf, v127
	v_fmac_f32_e32 v136, 0x3377d1cf, v128
	v_fmac_f32_e32 v137, 0x3377d1cf, v129
	v_fmac_f32_e32 v138, 0x3377d1cf, v130
	v_fmac_f32_e32 v139, 0x3377d1cf, v131
	v_fmac_f32_e32 v140, 0x3377d1cf, v132
	v_fmac_f32_e32 v141, 0x3377d1cf, v133
	v_fmac_f32_e32 v134, 0x3f317217, v126
	v_fmac_f32_e32 v135, 0x3f317217, v127
	v_fmac_f32_e32 v136, 0x3f317217, v128
	v_fmac_f32_e32 v137, 0x3f317217, v129
	v_fmac_f32_e32 v138, 0x3f317217, v130
	v_fmac_f32_e32 v139, 0x3f317217, v131
	v_fmac_f32_e32 v140, 0x3f317217, v132
	v_fmac_f32_e32 v141, 0x3f317217, v133
	v_sub_f32_e32 v142, v142, v134
	v_sub_f32_e32 v143, v143, v135
	v_sub_f32_e32 v144, v144, v136
	v_sub_f32_e32 v145, v145, v137
	v_sub_f32_e32 v146, v146, v138
	v_sub_f32_e32 v147, v147, v139
	v_sub_f32_e32 v148, v148, v140
	v_sub_f32_e32 v149, v149, v141
	v_mul_f32_e32 v142, s18, v142
	v_mul_f32_e32 v143, s18, v143
	v_mul_f32_e32 v144, s18, v144
	v_mul_f32_e32 v145, s18, v145
	v_mul_f32_e32 v146, s18, v146
	v_mul_f32_e32 v147, s18, v147
	v_mul_f32_e32 v148, s18, v148
	v_mul_f32_e32 v149, s18, v149
	ds_write2_b32 v37, v142, v143 offset0:0 offset1:1
	ds_write2_b32 v37, v144, v145 offset0:2 offset1:3
	ds_write2_b32 v37, v146, v147 offset0:4 offset1:5
	ds_write2_b32 v37, v148, v149 offset0:6 offset1:7
	ds_read_b128 v[94:97], v35 offset:43776
	ds_read_b128 v[98:101], v35 offset:43792
	ds_read_b128 v[118:121], v35 offset:39424
	ds_read_b128 v[122:125], v35 offset:39440
	ds_read_b128 v[126:129], v35 offset:39680
	ds_read_b128 v[130:133], v35 offset:39696
	ds_read_b128 v[134:137], v35 offset:39936
	ds_read_b128 v[138:141], v35 offset:39952
	ds_read_b128 v[142:145], v35 offset:40192
	ds_read_b128 v[146:149], v35 offset:40208
	v_lshlrev_b32_e32 v102, 16, v14
	v_and_b32_e32 v103, 0xffff0000, v14
	v_lshlrev_b32_e32 v104, 16, v15
	v_and_b32_e32 v105, 0xffff0000, v15
	v_lshlrev_b32_e32 v106, 16, v16
	v_and_b32_e32 v107, 0xffff0000, v16
	v_lshlrev_b32_e32 v108, 16, v17
	v_and_b32_e32 v109, 0xffff0000, v17
	v_lshlrev_b32_e32 v110, 16, v10
	v_and_b32_e32 v111, 0xffff0000, v10
	v_lshlrev_b32_e32 v112, 16, v11
	v_and_b32_e32 v113, 0xffff0000, v11
	v_lshlrev_b32_e32 v114, 16, v12
	v_and_b32_e32 v115, 0xffff0000, v12
	v_lshlrev_b32_e32 v116, 16, v13
	v_and_b32_e32 v117, 0xffff0000, v13
	s_waitcnt lgkmcnt(6)
	v_fmac_f32_e32 v94, v118, v102
	v_fmac_f32_e32 v95, v119, v102
	v_fmac_f32_e32 v96, v120, v102
	v_fmac_f32_e32 v97, v121, v102
	v_fmac_f32_e32 v98, v122, v102
	v_fmac_f32_e32 v99, v123, v102
	v_fmac_f32_e32 v100, v124, v102
	v_fmac_f32_e32 v101, v125, v102
	ds_read_b128 v[118:121], v35 offset:40448
	ds_read_b128 v[122:125], v35 offset:40464
	s_waitcnt lgkmcnt(6)
	v_fmac_f32_e32 v94, v126, v103
	v_fmac_f32_e32 v95, v127, v103
	v_fmac_f32_e32 v96, v128, v103
	v_fmac_f32_e32 v97, v129, v103
	v_fmac_f32_e32 v98, v130, v103
	v_fmac_f32_e32 v99, v131, v103
	v_fmac_f32_e32 v100, v132, v103
	v_fmac_f32_e32 v101, v133, v103
	ds_read_b128 v[126:129], v35 offset:40704
	ds_read_b128 v[130:133], v35 offset:40720
	s_waitcnt lgkmcnt(6)
; DI void gla_prep_item(const Args& A, int l, unsigned char* ldsb, int item, int tid, bool stage) {
;     ...
;             for (int r = 0; r < 16; ++r) {
;                 const f32x4 w0 = *(const f32x4*)(wg + dir * 1024 + r * 64 + 8 * dg), w1 = *(const f32x4*)(wg + dir * 1024 + r * 64 + 8 * dg + 4);
;                 const float cv = cf[dir * 16 + r];
;                 z[0] += cv * w0[0]; z[1] += cv * w0[1]; z[2] += cv * w0[2]; z[3] += cv * w0[3]; z[4] += cv * w1[0]; z[5] += cv * w1[1]; z[6] += cv * w1[2]; z[7] += cv * w1[3];
;             }
	v_fmac_f32_e32 v94, v134, v104
	v_fmac_f32_e32 v95, v135, v104
	v_fmac_f32_e32 v96, v136, v104
	v_fmac_f32_e32 v97, v137, v104
	v_fmac_f32_e32 v98, v138, v104
	v_fmac_f32_e32 v99, v139, v104
	v_fmac_f32_e32 v100, v140, v104
	v_fmac_f32_e32 v101, v141, v104
	ds_read_b128 v[134:137], v35 offset:40960
	ds_read_b128 v[138:141], v35 offset:40976
	s_waitcnt lgkmcnt(6)
	v_fmac_f32_e32 v94, v142, v105
	v_fmac_f32_e32 v95, v143, v105
	v_fmac_f32_e32 v96, v144, v105
	v_fmac_f32_e32 v97, v145, v105
	v_fmac_f32_e32 v98, v146, v105
	v_fmac_f32_e32 v99, v147, v105
	v_fmac_f32_e32 v100, v148, v105
	v_fmac_f32_e32 v101, v149, v105
	ds_read_b128 v[142:145], v35 offset:41216
	ds_read_b128 v[146:149], v35 offset:41232
	s_waitcnt lgkmcnt(6)
	v_fmac_f32_e32 v94, v118, v106
	v_fmac_f32_e32 v95, v119, v106
	v_fmac_f32_e32 v96, v120, v106
	v_fmac_f32_e32 v97, v121, v106
	v_fmac_f32_e32 v98, v122, v106
	v_fmac_f32_e32 v99, v123, v106
	v_fmac_f32_e32 v100, v124, v106
	v_fmac_f32_e32 v101, v125, v106
	ds_read_b128 v[118:121], v35 offset:41472
	ds_read_b128 v[122:125], v35 offset:41488
	s_waitcnt lgkmcnt(6)
	v_fmac_f32_e32 v94, v126, v107
	v_fmac_f32_e32 v95, v127, v107
	v_fmac_f32_e32 v96, v128, v107
	v_fmac_f32_e32 v97, v129, v107
	v_fmac_f32_e32 v98, v130, v107
	v_fmac_f32_e32 v99, v131, v107
	v_fmac_f32_e32 v100, v132, v107
	v_fmac_f32_e32 v101, v133, v107
	ds_read_b128 v[126:129], v35 offset:41728
	ds_read_b128 v[130:133], v35 offset:41744
	s_waitcnt lgkmcnt(6)
	v_fmac_f32_e32 v94, v134, v108
	v_fmac_f32_e32 v95, v135, v108
	v_fmac_f32_e32 v96, v136, v108
	v_fmac_f32_e32 v97, v137, v108
	v_fmac_f32_e32 v98, v138, v108
	v_fmac_f32_e32 v99, v139, v108
	v_fmac_f32_e32 v100, v140, v108
	v_fmac_f32_e32 v101, v141, v108
	ds_read_b128 v[134:137], v35 offset:41984
	ds_read_b128 v[138:141], v35 offset:42000
	s_waitcnt lgkmcnt(6)
	v_fmac_f32_e32 v94, v142, v109
	v_fmac_f32_e32 v95, v143, v109
	v_fmac_f32_e32 v96, v144, v109
	v_fmac_f32_e32 v97, v145, v109
	v_fmac_f32_e32 v98, v146, v109
	v_fmac_f32_e32 v99, v147, v109
	v_fmac_f32_e32 v100, v148, v109
	v_fmac_f32_e32 v101, v149, v109
	ds_read_b128 v[142:145], v35 offset:42240
	ds_read_b128 v[146:149], v35 offset:42256
	s_waitcnt lgkmcnt(6)
	v_fmac_f32_e32 v94, v118, v110
	v_fmac_f32_e32 v95, v119, v110
	v_fmac_f32_e32 v96, v120, v110
	v_fmac_f32_e32 v97, v121, v110
	v_fmac_f32_e32 v98, v122, v110
	v_fmac_f32_e32 v99, v123, v110
	v_fmac_f32_e32 v100, v124, v110
	v_fmac_f32_e32 v101, v125, v110
	ds_read_b128 v[118:121], v35 offset:42496
	ds_read_b128 v[122:125], v35 offset:42512
	s_waitcnt lgkmcnt(6)
	v_fmac_f32_e32 v94, v126, v111
	v_fmac_f32_e32 v95, v127, v111
	v_fmac_f32_e32 v96, v128, v111
	v_fmac_f32_e32 v97, v129, v111
	v_fmac_f32_e32 v98, v130, v111
	v_fmac_f32_e32 v99, v131, v111
	v_fmac_f32_e32 v100, v132, v111
	v_fmac_f32_e32 v101, v133, v111
	ds_read_b128 v[126:129], v35 offset:42752
	ds_read_b128 v[130:133], v35 offset:42768
	s_waitcnt lgkmcnt(6)
	v_fmac_f32_e32 v94, v134, v112
	v_fmac_f32_e32 v95, v135, v112
	v_fmac_f32_e32 v96, v136, v112
	v_fmac_f32_e32 v97, v137, v112
	v_fmac_f32_e32 v98, v138, v112
	v_fmac_f32_e32 v99, v139, v112
	v_fmac_f32_e32 v100, v140, v112
	v_fmac_f32_e32 v101, v141, v112
	ds_read_b128 v[134:137], v35 offset:43008
	ds_read_b128 v[138:141], v35 offset:43024
	s_waitcnt lgkmcnt(6)
	v_fmac_f32_e32 v94, v142, v113
	v_fmac_f32_e32 v95, v143, v113
	v_fmac_f32_e32 v96, v144, v113
	v_fmac_f32_e32 v97, v145, v113
	v_fmac_f32_e32 v98, v146, v113
	v_fmac_f32_e32 v99, v147, v113
	v_fmac_f32_e32 v100, v148, v113
	v_fmac_f32_e32 v101, v149, v113
	ds_read_b128 v[142:145], v35 offset:43264
	ds_read_b128 v[146:149], v35 offset:43280
	s_waitcnt lgkmcnt(6)
	v_fmac_f32_e32 v94, v118, v114
	v_fmac_f32_e32 v95, v119, v114
	v_fmac_f32_e32 v96, v120, v114
	v_fmac_f32_e32 v97, v121, v114
	v_fmac_f32_e32 v98, v122, v114
	v_fmac_f32_e32 v99, v123, v114
	v_fmac_f32_e32 v100, v124, v114
	v_fmac_f32_e32 v101, v125, v114
	s_waitcnt lgkmcnt(4)
	v_fmac_f32_e32 v94, v126, v115
	v_fmac_f32_e32 v95, v127, v115
	v_fmac_f32_e32 v96, v128, v115
	v_fmac_f32_e32 v97, v129, v115
	v_fmac_f32_e32 v98, v130, v115
	v_fmac_f32_e32 v99, v131, v115
	v_fmac_f32_e32 v100, v132, v115
	v_fmac_f32_e32 v101, v133, v115
	s_waitcnt lgkmcnt(2)
	v_fmac_f32_e32 v94, v134, v116
	v_fmac_f32_e32 v95, v135, v116
	v_fmac_f32_e32 v96, v136, v116
	v_fmac_f32_e32 v97, v137, v116
	v_fmac_f32_e32 v98, v138, v116
	v_fmac_f32_e32 v99, v139, v116
	v_fmac_f32_e32 v100, v140, v116
	v_fmac_f32_e32 v101, v141, v116
	s_waitcnt lgkmcnt(0)
; DI float log_sigmoid_f(float z) { return fminf(z, 0.f) - __logf(1.0f + __expf(-fabsf(z))); }
; DI void gla_prep_item(const Args& A, int l, unsigned char* ldsb, int item, int tid, bool stage) {
;     ...
;                 z[0] += cv * w0[0]; z[1] += cv * w0[1]; z[2] += cv * w0[2]; z[3] += cv * w0[3]; z[4] += cv * w1[0]; z[5] += cv * w1[1]; z[6] += cv * w1[2]; z[7] += cv * w1[3];
;             }
; #pragma unroll
;             for (int dd = 0; dd < 8; ++dd) gl[(dir * 64 + t) * 65 + 8 * dg + dd] = log_sigmoid_f(z[dd]) * (1.0f / 16.0f);
;         }
;     }
;     __syncthreads();
;     {
;         const int dir = tid >> 8, seg = (tid >> 6) & 3, d = tid & 63;
;         float* gp = gl + (dir * 64 + 16 * seg) * 65 + d; float v[16];
; #pragma unroll
;         for (int tt = 0; tt < 16; ++tt) v[tt] = gp[tt * 65];
;         if (dir == 0) {
; #pragma unroll
;             for (int tt = 1; tt < 16; ++tt) v[tt] += v[tt - 1];
;         } else {
; #pragma unroll
	v_fmac_f32_e32 v94, v142, v117
	v_fmac_f32_e32 v95, v143, v117
	v_fmac_f32_e32 v96, v144, v117
	v_fmac_f32_e32 v97, v145, v117
	v_fmac_f32_e32 v98, v146, v117
	v_fmac_f32_e32 v99, v147, v117
	v_fmac_f32_e32 v100, v148, v117
	v_fmac_f32_e32 v101, v149, v117
	v_mul_f32_e64 v118, |v94|, s11
	v_mul_f32_e64 v119, |v95|, s11
	v_mul_f32_e64 v120, |v96|, s11
	v_mul_f32_e64 v121, |v97|, s11
	v_mul_f32_e64 v122, |v98|, s11
	v_mul_f32_e64 v123, |v99|, s11
	v_mul_f32_e64 v124, |v100|, s11
	v_mul_f32_e64 v125, |v101|, s11
	v_exp_f32_e32 v118, v118
	v_exp_f32_e32 v119, v119
	v_exp_f32_e32 v120, v120
	v_exp_f32_e32 v121, v121
	v_exp_f32_e32 v122, v122
	v_exp_f32_e32 v123, v123
	v_exp_f32_e32 v124, v124
	v_exp_f32_e32 v125, v125
	v_min_f32_e32 v142, 0, v94
	v_min_f32_e32 v143, 0, v95
	v_min_f32_e32 v144, 0, v96
	v_min_f32_e32 v145, 0, v97
	v_min_f32_e32 v146, 0, v98
	v_min_f32_e32 v147, 0, v99
	v_min_f32_e32 v148, 0, v100
	v_min_f32_e32 v149, 0, v101
	v_add_f32_e32 v118, 1.0, v118
	v_add_f32_e32 v119, 1.0, v119
	v_add_f32_e32 v120, 1.0, v120
	v_add_f32_e32 v121, 1.0, v121
	v_add_f32_e32 v122, 1.0, v122
	v_add_f32_e32 v123, 1.0, v123
	v_add_f32_e32 v124, 1.0, v124
	v_add_f32_e32 v125, 1.0, v125
	v_log_f32_e32 v126, v118
	v_log_f32_e32 v127, v119
	v_log_f32_e32 v128, v120
	v_log_f32_e32 v129, v121
	v_log_f32_e32 v130, v122
	v_log_f32_e32 v131, v123
	v_log_f32_e32 v132, v124
	v_log_f32_e32 v133, v125
	s_nop 0
	v_mul_f32_e32 v134, 0x3f317217, v126
	v_mul_f32_e32 v135, 0x3f317217, v127
	v_mul_f32_e32 v136, 0x3f317217, v128
	v_mul_f32_e32 v137, 0x3f317217, v129
	v_mul_f32_e32 v138, 0x3f317217, v130
	v_mul_f32_e32 v139, 0x3f317217, v131
	v_mul_f32_e32 v140, 0x3f317217, v132
	v_mul_f32_e32 v141, 0x3f317217, v133
	v_fma_f32 v134, v126, s81, -v134
	v_fma_f32 v135, v127, s81, -v135
	v_fma_f32 v136, v128, s81, -v136
	v_fma_f32 v137, v129, s81, -v137
	v_fma_f32 v138, v130, s81, -v138
	v_fma_f32 v139, v131, s81, -v139
	v_fma_f32 v140, v132, s81, -v140
	v_fma_f32 v141, v133, s81, -v141
	v_fmac_f32_e32 v134, 0x3377d1cf, v126
	v_fmac_f32_e32 v135, 0x3377d1cf, v127
	v_fmac_f32_e32 v136, 0x3377d1cf, v128
	v_fmac_f32_e32 v137, 0x3377d1cf, v129
	v_fmac_f32_e32 v138, 0x3377d1cf, v130
	v_fmac_f32_e32 v139, 0x3377d1cf, v131
	v_fmac_f32_e32 v140, 0x3377d1cf, v132
	v_fmac_f32_e32 v141, 0x3377d1cf, v133
	v_fmac_f32_e32 v134, 0x3f317217, v126
	v_fmac_f32_e32 v135, 0x3f317217, v127
	v_fmac_f32_e32 v136, 0x3f317217, v128
	v_fmac_f32_e32 v137, 0x3f317217, v129
	v_fmac_f32_e32 v138, 0x3f317217, v130
	v_fmac_f32_e32 v139, 0x3f317217, v131
	v_fmac_f32_e32 v140, 0x3f317217, v132
	v_fmac_f32_e32 v141, 0x3f317217, v133
	v_sub_f32_e32 v142, v142, v134
	v_sub_f32_e32 v143, v143, v135
	v_sub_f32_e32 v144, v144, v136
	v_sub_f32_e32 v145, v145, v137
	v_sub_f32_e32 v146, v146, v138
	v_sub_f32_e32 v147, v147, v139
	v_sub_f32_e32 v148, v148, v140
	v_sub_f32_e32 v149, v149, v141
	v_mul_f32_e32 v142, s18, v142
	v_mul_f32_e32 v143, s18, v143
	v_mul_f32_e32 v144, s18, v144
	v_mul_f32_e32 v145, s18, v145
	v_mul_f32_e32 v146, s18, v146
	v_mul_f32_e32 v147, s18, v147
	v_mul_f32_e32 v148, s18, v148
	v_mul_f32_e32 v149, s18, v149
	v_add_u32_e32 v47, 0x4100, v37
	v_add_u32_e32 v45, 0x4108, v37
	v_add_u32_e32 v43, 0x4110, v37
	v_add_u32_e32 v0, 0x4118, v37
	v_add_u32_e32 v52, 0x400, v32
	v_add_u32_e32 v51, 0x800, v32
	v_add_u32_e32 v50, 0xc00, v32
	ds_write2_b32 v47, v142, v143 offset1:1
	ds_write2_b32 v45, v144, v145 offset1:1
	ds_write2_b32 v43, v146, v147 offset1:1
	ds_write2_b32 v0, v148, v149 offset1:1
	s_waitcnt lgkmcnt(0)
	s_barrier
	ds_read2_b32 v[12:13], v32 offset1:65
	ds_read2_b32 v[14:15], v32 offset0:130 offset1:195
	ds_read2_b32 v[16:17], v52 offset0:4 offset1:69
	ds_read2_b32 v[18:19], v52 offset0:134 offset1:199
	ds_read2_b32 v[20:21], v51 offset0:8 offset1:73
	ds_read2_b32 v[22:23], v51 offset0:138 offset1:203
	ds_read2_b32 v[24:25], v50 offset0:12 offset1:77
	ds_read2_b32 v[10:11], v50 offset0:142 offset1:207
	s_and_saveexec_b64 s[2:3], s[42:43]
	s_xor_b64 s[2:3], exec, s[2:3]
	s_cbranch_execz .LBB0_574
	s_waitcnt lgkmcnt(0)
	v_add_f32_e32 v53, v10, v11
	v_add_f32_e32 v54, v25, v53
	v_add_f32_e32 v55, v24, v54
	v_add_f32_e32 v56, v23, v55
	v_add_f32_e32 v57, v22, v56
	v_add_f32_e32 v58, v21, v57
	v_add_f32_e32 v59, v20, v58
	v_add_f32_e32 v60, v19, v59
	v_add_f32_e32 v61, v18, v60
	v_add_f32_e32 v62, v17, v61
	v_add_f32_e32 v63, v16, v62
	v_add_f32_e32 v80, v15, v63
	v_add_f32_e32 v81, v14, v80
	v_add_f32_e32 v82, v13, v81
	v_add_f32_e32 v84, v12, v82
